# LayerNorm phases: wave-wide sums via DPP quad_perm / row_mirror adds and v_permlane16/32_swap instead of six ds_bpermute round trips (bit-identical pairing order)
# baseline (speedup 1.0000x reference)
.LBB0_1129:
	s_or_b64 exec, exec, s[8:9]
	v_add_f32_e32 v67, v62, v63
	v_add_f32_e32 v76, v64, v65
	v_add_f32_e32 v67, v67, v76
	v_add_f32_e32 v76, v58, v59
	v_add_f32_e32 v77, v60, v61
	v_add_f32_e32 v67, 0, v67
	v_add_f32_e32 v76, v76, v77
	v_add_f32_e32 v67, v76, v67
	v_add_f32_e32 v76, v54, v55
	v_add_f32_e32 v77, v56, v57
	v_add_f32_e32 v76, v76, v77
	v_add_f32_e32 v67, v76, v67
	v_add_f32_e32 v76, v50, v51
	v_add_f32_e32 v77, v52, v53
	v_add_f32_e32 v76, v76, v77
	v_add_f32_e32 v67, v76, v67
	v_mov_b32_e32 v76, v0
	s_mov_b32 s3, 0x800000
	v_mbcnt_lo_u32_b32 v76, -1, v76
	v_mbcnt_hi_u32_b32 v76, -1, v76
	v_lshlrev_b32_e32 v76, 2, v76
	s_waitcnt lgkmcnt(0)
	s_nop 1
	v_add_f32_dpp v67, v67, v67 quad_perm:[1,0,3,2] row_mask:0xf bank_mask:0xf
	s_waitcnt lgkmcnt(0)
	s_nop 1
	v_add_f32_dpp v67, v67, v67 quad_perm:[2,3,0,1] row_mask:0xf bank_mask:0xf
	s_waitcnt lgkmcnt(0)
	s_nop 1
	v_add_f32_dpp v67, v67, v67 row_half_mirror row_mask:0xf bank_mask:0xf
	s_waitcnt lgkmcnt(0)
	s_nop 1
	v_add_f32_dpp v67, v67, v67 row_mirror row_mask:0xf bank_mask:0xf
	s_waitcnt lgkmcnt(0)
	v_mov_b32_e32 v77, v67
	v_mov_b32_e32 v76, v67
	s_nop 1
	v_permlane16_swap_b32 v77, v76
	s_nop 1
	v_add_f32_e32 v67, v77, v76
	s_waitcnt lgkmcnt(0)
	v_mov_b32_e32 v77, v67
	v_mov_b32_e32 v76, v67
	s_nop 1
	v_permlane32_swap_b32 v77, v76
	s_nop 1
	v_add_f32_e32 v67, v77, v76
	v_fmamk_f32 v81, v67, 0xba800000, v63
	v_fmamk_f32 v80, v67, 0xba800000, v62
	v_fmamk_f32 v65, v67, 0xba800000, v65
	v_fmac_f32_e32 v64, 0xba800000, v67
	v_pk_mul_f32 v[62:63], v[64:65], v[64:65]
	v_pk_mul_f32 v[76:77], v[80:81], v[80:81]
	v_fmamk_f32 v61, v67, 0xba800000, v61
	v_pk_mov_b32 v[78:79], v[76:77], v[62:63] op_sel:[1,0]
	v_mov_b32_e32 v77, v63
	v_pk_add_f32 v[62:63], v[78:79], v[76:77]
	v_fmamk_f32 v79, v67, 0xba800000, v59
	v_fmamk_f32 v78, v67, 0xba800000, v58
	v_fmac_f32_e32 v60, 0xba800000, v67
	v_pk_mul_f32 v[58:59], v[60:61], v[60:61]
	v_pk_mul_f32 v[76:77], v[78:79], v[78:79]
	v_fmac_f32_e32 v56, 0xba800000, v67
	v_pk_mov_b32 v[82:83], v[76:77], v[58:59] op_sel:[1,0]
	v_mov_b32_e32 v77, v59
	v_pk_add_f32 v[58:59], v[82:83], v[76:77]
	v_fmamk_f32 v76, v67, 0xba800000, v54
	v_fmamk_f32 v77, v67, 0xba800000, v55
	v_mul_f32_e32 v54, v76, v76
	v_pk_fma_f32 v[54:55], v[76:77], v[76:77], v[54:55] op_sel_hi:[1,1,0]
	v_fmamk_f32 v57, v67, 0xba800000, v57
	v_mul_f32_e32 v54, v56, v56
	v_pk_add_f32 v[62:63], v[62:63], v[62:63] op_sel_hi:[0,1]
	v_pk_add_f32 v[82:83], v[58:59], v[58:59] op_sel_hi:[0,1]
	v_pk_fma_f32 v[84:85], v[56:57], v[56:57], v[54:55] op_sel_hi:[1,1,0]
	v_fmamk_f32 v59, v67, 0xba800000, v53
	v_fmamk_f32 v58, v67, 0xba800000, v52
	v_fmamk_f32 v51, v67, 0xba800000, v51
	v_fmac_f32_e32 v50, 0xba800000, v67
	v_mul_f32_e32 v54, v50, v50
	v_mul_f32_e32 v84, v51, v51
	v_mul_f32_e32 v62, v58, v58
	v_mul_f32_e32 v82, v59, v59
	v_pk_add_f32 v[52:53], v[54:55], v[84:85]
	v_pk_add_f32 v[54:55], v[62:63], v[82:83]
	s_nop 0
	v_pk_add_f32 v[52:53], v[52:53], v[54:55]
	s_nop 0
	v_add_f32_e32 v52, v52, v53
	v_mov_b32_e32 v53, v0
	s_nop 0
	v_mbcnt_lo_u32_b32 v53, -1, v53
	v_mbcnt_hi_u32_b32 v53, -1, v53
	v_lshlrev_b32_e32 v53, 2, v53
	s_waitcnt lgkmcnt(0)
	s_nop 1
	v_add_f32_dpp v52, v52, v52 quad_perm:[1,0,3,2] row_mask:0xf bank_mask:0xf
	s_waitcnt lgkmcnt(0)
	s_nop 1
	v_add_f32_dpp v52, v52, v52 quad_perm:[2,3,0,1] row_mask:0xf bank_mask:0xf
	s_waitcnt lgkmcnt(0)
	s_nop 1
	v_add_f32_dpp v52, v52, v52 row_half_mirror row_mask:0xf bank_mask:0xf
	s_waitcnt lgkmcnt(0)
	s_nop 1
	v_add_f32_dpp v52, v52, v52 row_mirror row_mask:0xf bank_mask:0xf
	s_waitcnt lgkmcnt(0)
	v_mov_b32_e32 v54, v52
	v_mov_b32_e32 v53, v52
	s_nop 1
	v_permlane16_swap_b32 v54, v53
	s_nop 1
	v_add_f32_e32 v52, v54, v53
	s_waitcnt lgkmcnt(0)
	v_mov_b32_e32 v54, v52
	v_mov_b32_e32 v53, v52
	s_nop 1
	v_permlane32_swap_b32 v54, v53
	s_nop 1
	v_add_f32_e32 v52, v54, v53
	v_fmamk_f32 v52, v52, 0x3a800000, v217
	v_cmp_gt_f32_e32 vcc, s3, v52
	v_mul_f32_e32 v53, 0x4b800000, v52
	s_nop 0
	v_cndmask_b32_e32 v52, v52, v53, vcc
	v_rsq_f32_e32 v52, v52
	s_nop 0
	v_mul_f32_e32 v53, 0x45800000, v52
	v_cndmask_b32_e32 v62, v52, v53, vcc
	v_pk_mul_f32 v[52:53], v[80:81], v[62:63] op_sel_hi:[1,0]
	v_pk_mul_f32 v[54:55], v[64:65], v[62:63] op_sel_hi:[1,0]
	v_pk_fma_f32 v[52:53], v[2:3], v[52:53], v[10:11]
	v_pk_fma_f32 v[54:55], v[4:5], v[54:55], v[12:13]
	global_store_dwordx4 v[74:75], v[52:55], off offset:-3072
	v_cvt_pk_bf16_f32 v64, v52, v53
	v_cvt_pk_bf16_f32 v65, v54, v55
	ds_read_b128 v[80:83], v1
	global_store_dwordx2 v[70:71], v[64:65], off offset:-1536
	ds_read_b128 v[92:95], v1 offset:49152
	s_waitcnt lgkmcnt(1)
	v_mul_f32_e32 v63, v81, v53
	v_mul_f32_e32 v64, v83, v55
	v_fmac_f32_e32 v63, v80, v52
	v_fmac_f32_e32 v64, v82, v54
	ds_read_b128 v[80:83], v1 offset:4096
	v_add_f32_e32 v63, v63, v64
	v_add_f32_e32 v91, 0, v63
	s_waitcnt lgkmcnt(0)
	v_mul_f32_e32 v63, v81, v53
	v_mul_f32_e32 v64, v83, v55
	v_fmac_f32_e32 v63, v80, v52
	v_fmac_f32_e32 v64, v82, v54
	ds_read_b128 v[80:83], v1 offset:8192
	v_add_f32_e32 v63, v63, v64
	v_add_f32_e32 v63, 0, v63
	s_waitcnt lgkmcnt(0)
	v_mul_f32_e32 v64, v81, v53
	v_mul_f32_e32 v65, v83, v55
	v_fmac_f32_e32 v64, v80, v52
	v_fmac_f32_e32 v65, v82, v54
	ds_read_b128 v[80:83], v1 offset:12288
	v_add_f32_e32 v64, v64, v65
	v_add_f32_e32 v64, 0, v64
	s_waitcnt lgkmcnt(0)
	v_mul_f32_e32 v65, v81, v53
	v_mul_f32_e32 v67, v83, v55
	v_fmac_f32_e32 v65, v80, v52
	v_fmac_f32_e32 v67, v82, v54
	ds_read_b128 v[80:83], v1 offset:16384
	v_add_f32_e32 v65, v65, v67
	v_add_f32_e32 v65, 0, v65
	s_waitcnt lgkmcnt(0)
	v_mul_f32_e32 v67, v81, v53
	v_fmac_f32_e32 v67, v80, v52
	v_mul_f32_e32 v80, v83, v55
	v_fmac_f32_e32 v80, v82, v54
	v_add_f32_e32 v67, v67, v80
	ds_read_b128 v[80:83], v1 offset:20480
	v_add_f32_e32 v67, 0, v67
	s_waitcnt lgkmcnt(0)
	v_mul_f32_e32 v81, v81, v53
	v_fmac_f32_e32 v81, v80, v52
	v_mul_f32_e32 v80, v83, v55
	v_fmac_f32_e32 v80, v82, v54
	ds_read_b128 v[82:85], v1 offset:24576
	v_add_f32_e32 v80, v81, v80
	v_add_f32_e32 v80, 0, v80
	s_waitcnt lgkmcnt(0)
	v_mul_f32_e32 v81, v83, v53
	v_fmac_f32_e32 v81, v82, v52
	v_mul_f32_e32 v82, v85, v55
	v_fmac_f32_e32 v82, v84, v54
	v_add_f32_e32 v81, v81, v82
	ds_read_b128 v[82:85], v1 offset:28672
	v_add_f32_e32 v81, 0, v81
	s_waitcnt lgkmcnt(0)
	v_mul_f32_e32 v83, v83, v53
	v_fmac_f32_e32 v83, v82, v52
	v_mul_f32_e32 v82, v85, v55
	v_fmac_f32_e32 v82, v84, v54
	ds_read_b128 v[84:87], v1 offset:32768
	v_add_f32_e32 v82, v83, v82
	v_add_f32_e32 v82, 0, v82
	s_waitcnt lgkmcnt(0)
	v_mul_f32_e32 v83, v85, v53
	v_fmac_f32_e32 v83, v84, v52
	v_mul_f32_e32 v84, v87, v55
	v_fmac_f32_e32 v84, v86, v54
	v_add_f32_e32 v83, v83, v84
	ds_read_b128 v[84:87], v1 offset:36864
	v_add_f32_e32 v83, 0, v83
	s_waitcnt lgkmcnt(0)
	v_mul_f32_e32 v85, v85, v53
	v_fmac_f32_e32 v85, v84, v52
	v_mul_f32_e32 v84, v87, v55
	v_fmac_f32_e32 v84, v86, v54
	ds_read_b128 v[86:89], v1 offset:40960
	v_add_f32_e32 v84, v85, v84
	v_add_f32_e32 v84, 0, v84
	s_waitcnt lgkmcnt(0)
	v_mul_f32_e32 v85, v87, v53
	v_fmac_f32_e32 v85, v86, v52
	v_mul_f32_e32 v86, v89, v55
	v_fmac_f32_e32 v86, v88, v54
	v_add_f32_e32 v85, v85, v86
	ds_read_b128 v[86:89], v1 offset:45056
	v_add_f32_e32 v85, 0, v85
	s_waitcnt lgkmcnt(0)
	v_mul_f32_e32 v87, v87, v53
	v_fmac_f32_e32 v87, v86, v52
	v_mul_f32_e32 v86, v89, v55
	v_fmac_f32_e32 v86, v88, v54
	v_add_f32_e32 v86, v87, v86
	v_mul_f32_e32 v87, v93, v53
	v_mul_f32_e32 v88, v95, v55
	v_fmac_f32_e32 v87, v92, v52
	v_fmac_f32_e32 v88, v94, v54
	ds_read_b128 v[92:95], v1 offset:53248
	v_add_f32_e32 v87, v87, v88
	v_add_f32_e32 v86, 0, v86
	v_add_f32_e32 v87, 0, v87
	s_waitcnt lgkmcnt(0)
	v_mul_f32_e32 v88, v93, v53
	v_mul_f32_e32 v89, v95, v55
	v_fmac_f32_e32 v88, v92, v52
	v_fmac_f32_e32 v89, v94, v54
	ds_read_b128 v[92:95], v1 offset:57344
	v_add_f32_e32 v88, v88, v89
	v_add_f32_e32 v88, 0, v88
	s_waitcnt lgkmcnt(0)
	v_mul_f32_e32 v89, v93, v53
	v_mul_f32_e32 v90, v95, v55
	v_fmac_f32_e32 v89, v92, v52
	v_fmac_f32_e32 v90, v94, v54
	ds_read_b128 v[92:95], v1 offset:61440
	v_add_f32_e32 v89, v89, v90
	v_add_f32_e32 v89, 0, v89
	s_waitcnt lgkmcnt(0)
	v_mul_f32_e32 v53, v93, v53
	v_fmac_f32_e32 v53, v92, v52
	v_mul_f32_e32 v52, v95, v55
	v_fmac_f32_e32 v52, v94, v54
	v_add_f32_e32 v52, v53, v52
	v_add_f32_e32 v90, 0, v52
	v_pk_mul_f32 v[52:53], v[78:79], v[62:63] op_sel_hi:[1,0]
	v_pk_mul_f32 v[54:55], v[60:61], v[62:63] op_sel_hi:[1,0]
	v_pk_fma_f32 v[52:53], v[6:7], v[52:53], v[14:15]
	v_pk_fma_f32 v[54:55], v[8:9], v[54:55], v[16:17]
	global_store_dwordx4 v[74:75], v[52:55], off offset:-2048
	v_cvt_pk_bf16_f32 v60, v52, v53
	v_cvt_pk_bf16_f32 v61, v54, v55
	ds_read_b128 v[92:95], v1 offset:1024
	global_store_dwordx2 v[70:71], v[60:61], off offset:-1024
	s_waitcnt lgkmcnt(0)
	v_mul_f32_e32 v60, v53, v93
	v_mul_f32_e32 v61, v55, v95
	v_fmac_f32_e32 v60, v52, v92
	v_fmac_f32_e32 v61, v54, v94
	ds_read_b128 v[92:95], v1 offset:5120
	v_add_f32_e32 v60, v60, v61
	v_add_f32_e32 v60, v91, v60
	s_waitcnt lgkmcnt(0)
	v_mul_f32_e32 v61, v53, v93
	v_mul_f32_e32 v78, v55, v95
	v_fmac_f32_e32 v61, v52, v92
	v_fmac_f32_e32 v78, v54, v94
	ds_read_b128 v[92:95], v1 offset:9216
	v_add_f32_e32 v61, v61, v78
	v_add_f32_e32 v61, v63, v61
	s_waitcnt lgkmcnt(0)
	v_mul_f32_e32 v63, v53, v93
	v_mul_f32_e32 v78, v55, v95
	v_fmac_f32_e32 v63, v52, v92
	v_fmac_f32_e32 v78, v54, v94
	ds_read_b128 v[92:95], v1 offset:13312
	v_add_f32_e32 v63, v63, v78
	v_add_f32_e32 v63, v64, v63
	s_waitcnt lgkmcnt(0)
	v_mul_f32_e32 v64, v53, v93
	v_mul_f32_e32 v78, v55, v95
	v_fmac_f32_e32 v64, v52, v92
	v_fmac_f32_e32 v78, v54, v94
	ds_read_b128 v[92:95], v1 offset:17408
	v_add_f32_e32 v64, v64, v78
	v_add_f32_e32 v64, v65, v64
	s_waitcnt lgkmcnt(0)
	v_mul_f32_e32 v65, v53, v93
	v_mul_f32_e32 v78, v55, v95
	v_fmac_f32_e32 v65, v52, v92
	v_fmac_f32_e32 v78, v54, v94
	ds_read_b128 v[92:95], v1 offset:21504
	v_add_f32_e32 v65, v65, v78
	v_add_f32_e32 v65, v67, v65
	s_waitcnt lgkmcnt(0)
	v_mul_f32_e32 v67, v53, v93
	v_mul_f32_e32 v78, v55, v95
	v_fmac_f32_e32 v67, v52, v92
	v_fmac_f32_e32 v78, v54, v94
	ds_read_b128 v[92:95], v1 offset:25600
	v_add_f32_e32 v67, v67, v78
	v_add_f32_e32 v67, v80, v67
	s_waitcnt lgkmcnt(0)
	v_mul_f32_e32 v78, v53, v93
	v_mul_f32_e32 v79, v55, v95
	v_fmac_f32_e32 v78, v52, v92
	v_fmac_f32_e32 v79, v54, v94
	ds_read_b128 v[92:95], v1 offset:29696
	v_add_f32_e32 v78, v78, v79
	v_add_f32_e32 v78, v81, v78
	s_waitcnt lgkmcnt(0)
	v_mul_f32_e32 v79, v53, v93
	v_mul_f32_e32 v80, v55, v95
	v_fmac_f32_e32 v79, v52, v92
	v_fmac_f32_e32 v80, v54, v94
	ds_read_b128 v[92:95], v1 offset:33792
	v_add_f32_e32 v79, v79, v80
	v_add_f32_e32 v79, v82, v79
	s_waitcnt lgkmcnt(0)
	v_mul_f32_e32 v80, v53, v93
	v_mul_f32_e32 v81, v55, v95
	v_fmac_f32_e32 v80, v52, v92
	v_fmac_f32_e32 v81, v54, v94
	ds_read_b128 v[92:95], v1 offset:37888
	v_add_f32_e32 v80, v80, v81
	v_add_f32_e32 v80, v83, v80
	s_waitcnt lgkmcnt(0)
	v_mul_f32_e32 v81, v53, v93
	v_mul_f32_e32 v82, v55, v95
	v_fmac_f32_e32 v81, v52, v92
	v_fmac_f32_e32 v82, v54, v94
	ds_read_b128 v[92:95], v1 offset:41984
	v_add_f32_e32 v81, v81, v82
	v_add_f32_e32 v81, v84, v81
	s_waitcnt lgkmcnt(0)
	v_mul_f32_e32 v82, v53, v93
	v_mul_f32_e32 v83, v55, v95
	v_fmac_f32_e32 v82, v52, v92
	v_fmac_f32_e32 v83, v54, v94
	ds_read_b128 v[92:95], v1 offset:46080
	v_add_f32_e32 v82, v82, v83
	v_add_f32_e32 v82, v85, v82
	s_waitcnt lgkmcnt(0)
	v_mul_f32_e32 v83, v53, v93
	v_mul_f32_e32 v84, v55, v95
	v_fmac_f32_e32 v83, v52, v92
	v_fmac_f32_e32 v84, v54, v94
	ds_read_b128 v[92:95], v1 offset:50176
	v_add_f32_e32 v83, v83, v84
	v_add_f32_e32 v83, v86, v83
	s_waitcnt lgkmcnt(0)
	v_mul_f32_e32 v84, v53, v93
	v_mul_f32_e32 v85, v55, v95
	v_fmac_f32_e32 v84, v52, v92
	v_fmac_f32_e32 v85, v54, v94
	ds_read_b128 v[92:95], v1 offset:54272
	v_add_f32_e32 v84, v84, v85
	v_add_f32_e32 v84, v87, v84
	s_waitcnt lgkmcnt(0)
	v_mul_f32_e32 v85, v53, v93
	v_mul_f32_e32 v86, v55, v95
	v_fmac_f32_e32 v85, v52, v92
	v_fmac_f32_e32 v86, v54, v94
	ds_read_b128 v[92:95], v1 offset:58368
	v_add_f32_e32 v85, v85, v86
	v_add_f32_e32 v85, v88, v85
	s_waitcnt lgkmcnt(0)
	v_mul_f32_e32 v86, v53, v93
	v_mul_f32_e32 v87, v55, v95
	v_fmac_f32_e32 v86, v52, v92
	v_fmac_f32_e32 v87, v54, v94
	ds_read_b128 v[92:95], v1 offset:62464
	v_add_f32_e32 v86, v86, v87
	v_add_f32_e32 v86, v89, v86
	s_waitcnt lgkmcnt(0)
	v_mul_f32_e32 v53, v53, v93
	v_fmac_f32_e32 v53, v52, v92
	v_mul_f32_e32 v52, v55, v95
	v_fmac_f32_e32 v52, v54, v94
	v_add_f32_e32 v52, v53, v52
	v_add_f32_e32 v87, v90, v52
	v_pk_mul_f32 v[52:53], v[76:77], v[62:63] op_sel_hi:[1,0]
	v_pk_mul_f32 v[54:55], v[56:57], v[62:63] op_sel_hi:[1,0]
	s_waitcnt vmcnt(5)
	v_pk_fma_f32 v[52:53], v[26:27], v[52:53], v[18:19]
	v_pk_fma_f32 v[54:55], v[28:29], v[54:55], v[20:21]
	global_store_dwordx4 v[74:75], v[52:55], off offset:-1024
	v_cvt_pk_bf16_f32 v56, v52, v53
	v_cvt_pk_bf16_f32 v57, v54, v55
	ds_read_b128 v[88:91], v1 offset:2048
	global_store_dwordx2 v[70:71], v[56:57], off offset:-512
	s_waitcnt lgkmcnt(0)
	v_mul_f32_e32 v56, v53, v89
	v_mul_f32_e32 v57, v55, v91
	v_fmac_f32_e32 v56, v52, v88
	v_fmac_f32_e32 v57, v54, v90
	ds_read_b128 v[88:91], v1 offset:6144
	v_add_f32_e32 v56, v56, v57
	v_add_f32_e32 v56, v60, v56
	s_waitcnt lgkmcnt(0)
	v_mul_f32_e32 v57, v53, v89
	v_mul_f32_e32 v60, v55, v91
	v_fmac_f32_e32 v57, v52, v88
	v_fmac_f32_e32 v60, v54, v90
	ds_read_b128 v[88:91], v1 offset:10240
	v_add_f32_e32 v57, v57, v60
	v_add_f32_e32 v57, v61, v57
	s_waitcnt lgkmcnt(0)
	v_mul_f32_e32 v60, v53, v89
	v_mul_f32_e32 v61, v55, v91
	v_fmac_f32_e32 v60, v52, v88
	v_fmac_f32_e32 v61, v54, v90
	ds_read_b128 v[88:91], v1 offset:14336
	v_add_f32_e32 v60, v60, v61
	v_add_f32_e32 v60, v63, v60
	s_waitcnt lgkmcnt(0)
	v_mul_f32_e32 v61, v53, v89
	v_mul_f32_e32 v63, v55, v91
	v_fmac_f32_e32 v61, v52, v88
	v_fmac_f32_e32 v63, v54, v90
	ds_read_b128 v[88:91], v1 offset:18432
	v_add_f32_e32 v61, v61, v63
	v_add_f32_e32 v61, v64, v61
	s_waitcnt lgkmcnt(0)
	v_mul_f32_e32 v63, v53, v89
	v_mul_f32_e32 v64, v55, v91
	v_fmac_f32_e32 v63, v52, v88
	v_fmac_f32_e32 v64, v54, v90
	ds_read_b128 v[88:91], v1 offset:22528
	v_add_f32_e32 v63, v63, v64
	v_add_f32_e32 v63, v65, v63
	v_pk_mul_f32 v[50:51], v[50:51], v[62:63] op_sel_hi:[1,0]
	s_waitcnt lgkmcnt(0)
	v_mul_f32_e32 v64, v53, v89
	v_mul_f32_e32 v65, v55, v91
	v_fmac_f32_e32 v64, v52, v88
	v_fmac_f32_e32 v65, v54, v90
	ds_read_b128 v[88:91], v1 offset:26624
	v_add_f32_e32 v64, v64, v65
	v_add_f32_e32 v64, v67, v64
	s_waitcnt vmcnt(6)
	v_pk_fma_f32 v[50:51], v[30:31], v[50:51], v[22:23]
	s_waitcnt lgkmcnt(0)
	v_mul_f32_e32 v65, v53, v89
	v_mul_f32_e32 v67, v55, v91
	v_fmac_f32_e32 v65, v52, v88
	v_fmac_f32_e32 v67, v54, v90
	ds_read_b128 v[88:91], v1 offset:30720
	v_add_f32_e32 v65, v65, v67
	v_add_f32_e32 v65, v78, v65
	s_waitcnt lgkmcnt(0)
	v_mul_f32_e32 v67, v53, v89
	v_mul_f32_e32 v76, v55, v91
	v_fmac_f32_e32 v67, v52, v88
	v_fmac_f32_e32 v76, v54, v90
	v_add_f32_e32 v67, v67, v76
	v_add_f32_e32 v67, v79, v67
	ds_read_b128 v[76:79], v1 offset:34816
	ds_read_b128 v[88:91], v1 offset:38912
	s_waitcnt lgkmcnt(1)
	v_mul_f32_e32 v77, v53, v77
	v_fmac_f32_e32 v77, v52, v76
	v_mul_f32_e32 v76, v55, v79
	v_fmac_f32_e32 v76, v54, v78
	v_add_f32_e32 v76, v77, v76
	s_waitcnt lgkmcnt(0)
	v_mul_f32_e32 v77, v53, v89
	v_mul_f32_e32 v78, v55, v91
	v_fmac_f32_e32 v77, v52, v88
	v_fmac_f32_e32 v78, v54, v90
	v_add_f32_e32 v77, v77, v78
	v_add_f32_e32 v76, v80, v76
	v_add_f32_e32 v77, v81, v77
	ds_read_b128 v[78:81], v1 offset:43008
	ds_read_b128 v[88:91], v1 offset:47104
	s_waitcnt lgkmcnt(1)
	v_mul_f32_e32 v79, v53, v79
	v_fmac_f32_e32 v79, v52, v78
	v_mul_f32_e32 v78, v55, v81
	v_fmac_f32_e32 v78, v54, v80
	v_add_f32_e32 v78, v79, v78
	s_waitcnt lgkmcnt(0)
	v_mul_f32_e32 v79, v53, v89
	v_mul_f32_e32 v80, v55, v91
	v_fmac_f32_e32 v79, v52, v88
	v_fmac_f32_e32 v80, v54, v90
	v_add_f32_e32 v79, v79, v80
	v_add_f32_e32 v78, v82, v78
	v_add_f32_e32 v79, v83, v79
	ds_read_b128 v[80:83], v1 offset:51200
	ds_read_b128 v[88:91], v1 offset:55296
	s_waitcnt lgkmcnt(1)
	v_mul_f32_e32 v81, v53, v81
	v_fmac_f32_e32 v81, v52, v80
	v_mul_f32_e32 v80, v55, v83
	v_fmac_f32_e32 v80, v54, v82
	v_add_f32_e32 v80, v81, v80
	s_waitcnt lgkmcnt(0)
	v_mul_f32_e32 v81, v53, v89
	v_mul_f32_e32 v82, v55, v91
	v_fmac_f32_e32 v81, v52, v88
	v_fmac_f32_e32 v82, v54, v90
	v_add_f32_e32 v81, v81, v82
	v_add_f32_e32 v80, v84, v80
	v_add_f32_e32 v81, v85, v81
	ds_read_b128 v[82:85], v1 offset:59392
	ds_read_b128 v[88:91], v1 offset:63488
	s_waitcnt lgkmcnt(1)
	v_mul_f32_e32 v83, v53, v83
	s_waitcnt lgkmcnt(0)
	v_mul_f32_e32 v53, v53, v89
	v_fmac_f32_e32 v83, v52, v82
	v_fmac_f32_e32 v53, v52, v88
	v_mul_f32_e32 v52, v55, v91
	v_fmac_f32_e32 v52, v54, v90
	v_mul_f32_e32 v82, v55, v85
	v_add_f32_e32 v52, v53, v52
	v_fmac_f32_e32 v82, v54, v84
	v_add_f32_e32 v54, v87, v52
	v_pk_mul_f32 v[52:53], v[58:59], v[62:63] op_sel_hi:[1,0]
	v_add_f32_e32 v82, v83, v82
	v_pk_fma_f32 v[52:53], v[32:33], v[52:53], v[24:25]
	v_add_f32_e32 v82, v86, v82
	global_store_dwordx4 v[74:75], v[50:53], off
	v_cvt_pk_bf16_f32 v58, v50, v51
	v_cvt_pk_bf16_f32 v59, v52, v53
	ds_read_b128 v[84:87], v1 offset:3072
	global_store_dwordx2 v[70:71], v[58:59], off
	s_waitcnt lgkmcnt(0)
	v_mul_f32_e32 v55, v51, v85
	v_mul_f32_e32 v58, v53, v87
	v_fmac_f32_e32 v55, v50, v84
	v_fmac_f32_e32 v58, v52, v86
	ds_read_b128 v[84:87], v1 offset:7168
	v_add_f32_e32 v55, v55, v58
	v_add_f32_e32 v55, v56, v55
	s_waitcnt lgkmcnt(0)
	v_mul_f32_e32 v56, v51, v85
	v_mul_f32_e32 v58, v53, v87
	v_fmac_f32_e32 v56, v50, v84
	v_fmac_f32_e32 v58, v52, v86
	ds_read_b128 v[84:87], v1 offset:11264
	v_add_f32_e32 v56, v56, v58
	v_add_f32_e32 v56, v57, v56
	s_waitcnt lgkmcnt(0)
	v_mul_f32_e32 v57, v51, v85
	v_mul_f32_e32 v58, v53, v87
	v_fmac_f32_e32 v57, v50, v84
	v_fmac_f32_e32 v58, v52, v86
	ds_read_b128 v[84:87], v1 offset:15360
	v_add_f32_e32 v57, v57, v58
	v_add_f32_e32 v57, v60, v57
	s_waitcnt lgkmcnt(0)
	v_mul_f32_e32 v58, v51, v85
	v_mul_f32_e32 v59, v53, v87
	v_fmac_f32_e32 v58, v50, v84
	v_fmac_f32_e32 v59, v52, v86
	ds_read_b128 v[84:87], v1 offset:19456
	v_add_f32_e32 v58, v58, v59
	v_add_f32_e32 v58, v61, v58
	s_waitcnt lgkmcnt(0)
	v_mul_f32_e32 v59, v51, v85
	v_mul_f32_e32 v60, v53, v87
	v_fmac_f32_e32 v59, v50, v84
	v_fmac_f32_e32 v60, v52, v86
	v_add_f32_e32 v59, v59, v60
	v_add_f32_e32 v59, v63, v59
	ds_read_b128 v[60:63], v1 offset:23552
	ds_read_b128 v[84:87], v1 offset:27648
	s_waitcnt lgkmcnt(1)
	v_mul_f32_e32 v61, v51, v61
	v_fmac_f32_e32 v61, v50, v60
	v_mul_f32_e32 v60, v53, v63
	v_fmac_f32_e32 v60, v52, v62
	v_add_f32_e32 v60, v61, v60
	v_add_f32_e32 v61, v64, v60
	s_waitcnt lgkmcnt(0)
	v_mul_f32_e32 v60, v51, v85
	v_mul_f32_e32 v62, v53, v87
	v_fmac_f32_e32 v60, v50, v84
	v_fmac_f32_e32 v62, v52, v86
	v_add_f32_e32 v60, v60, v62
	v_add_f32_e32 v60, v65, v60
	ds_read_b128 v[62:65], v1 offset:31744
	s_waitcnt lgkmcnt(0)
	v_mul_f32_e32 v63, v51, v63
	v_fmac_f32_e32 v63, v50, v62
	v_mul_f32_e32 v62, v53, v65
	v_fmac_f32_e32 v62, v52, v64
	v_add_f32_e32 v62, v63, v62
	v_add_f32_e32 v67, v67, v62
	ds_read_b128 v[62:65], v1 offset:35840
	s_waitcnt lgkmcnt(0)
	v_mul_f32_e32 v63, v51, v63
	v_fmac_f32_e32 v63, v50, v62
	v_mul_f32_e32 v62, v53, v65
	v_fmac_f32_e32 v62, v52, v64
	v_add_f32_e32 v62, v63, v62
	v_add_f32_e32 v76, v76, v62
	ds_read_b128 v[62:65], v1 offset:39936
	s_waitcnt lgkmcnt(0)
	v_mul_f32_e32 v63, v51, v63
	v_fmac_f32_e32 v63, v50, v62
	v_mul_f32_e32 v62, v53, v65
	v_fmac_f32_e32 v62, v52, v64
	v_add_f32_e32 v62, v63, v62
	v_add_f32_e32 v77, v77, v62
	ds_read_b128 v[62:65], v1 offset:44032
	s_waitcnt lgkmcnt(0)
	v_mul_f32_e32 v63, v51, v63
	v_fmac_f32_e32 v63, v50, v62
	v_mul_f32_e32 v62, v53, v65
	v_fmac_f32_e32 v62, v52, v64
	v_add_f32_e32 v62, v63, v62
	v_add_f32_e32 v78, v78, v62
	ds_read_b128 v[62:65], v1 offset:48128
	s_waitcnt lgkmcnt(0)
	v_mul_f32_e32 v63, v51, v63
	v_fmac_f32_e32 v63, v50, v62
	v_mul_f32_e32 v62, v53, v65
	v_fmac_f32_e32 v62, v52, v64
	v_add_f32_e32 v62, v63, v62
	v_add_f32_e32 v79, v79, v62
	ds_read_b128 v[62:65], v1 offset:52224
	s_waitcnt lgkmcnt(0)
	v_mul_f32_e32 v63, v51, v63
	v_fmac_f32_e32 v63, v50, v62
	v_mul_f32_e32 v62, v53, v65
	v_fmac_f32_e32 v62, v52, v64
	v_add_f32_e32 v62, v63, v62
	v_add_f32_e32 v80, v80, v62
	ds_read_b128 v[62:65], v1 offset:56320
	s_waitcnt lgkmcnt(0)
	v_mul_f32_e32 v63, v51, v63
	v_fmac_f32_e32 v63, v50, v62
	v_mul_f32_e32 v62, v53, v65
	v_fmac_f32_e32 v62, v52, v64
	v_add_f32_e32 v62, v63, v62
	v_add_f32_e32 v81, v81, v62
	ds_read_b128 v[62:65], v1 offset:60416
	s_waitcnt lgkmcnt(0)
	v_mul_f32_e32 v63, v51, v63
	v_fmac_f32_e32 v63, v50, v62
	v_mul_f32_e32 v62, v53, v65
	v_fmac_f32_e32 v62, v52, v64
	v_add_f32_e32 v62, v63, v62
	v_add_f32_e32 v82, v82, v62
	ds_read_b128 v[62:65], v1 offset:64512
	s_waitcnt lgkmcnt(0)
	v_mul_f32_e32 v51, v51, v63
	v_fmac_f32_e32 v51, v50, v62
	v_mul_f32_e32 v50, v53, v65
	v_fmac_f32_e32 v50, v52, v64
	v_add_f32_e32 v50, v51, v50
	v_add_f32_e32 v51, v54, v50
	v_mov_b32_e32 v50, v0
	s_nop 0
	v_mbcnt_lo_u32_b32 v50, -1, v50
	v_mbcnt_hi_u32_b32 v50, -1, v50
	v_and_b32_e32 v52, 32, v50
	v_cmp_eq_u32_e32 vcc, 0, v52
	v_lshlrev_b32_e32 v52, 2, v50
	v_xor_b32_e32 v53, 0x80, v52
	v_cndmask_b32_e32 v54, v55, v76, vcc
	ds_bpermute_b32 v54, v53, v54
	v_cndmask_b32_e32 v55, v76, v55, vcc
	s_waitcnt lgkmcnt(0)
	v_add_f32_e32 v54, v55, v54
	v_cndmask_b32_e32 v55, v56, v77, vcc
	ds_bpermute_b32 v55, v53, v55
	v_cndmask_b32_e32 v56, v77, v56, vcc
	s_waitcnt lgkmcnt(0)
	v_add_f32_e32 v55, v56, v55
	v_cndmask_b32_e32 v56, v57, v78, vcc
	ds_bpermute_b32 v56, v53, v56
	v_cndmask_b32_e32 v57, v78, v57, vcc
	s_waitcnt lgkmcnt(0)
	v_add_f32_e32 v56, v57, v56
	v_cndmask_b32_e32 v57, v58, v79, vcc
	ds_bpermute_b32 v57, v53, v57
	v_cndmask_b32_e32 v58, v79, v58, vcc
	s_waitcnt lgkmcnt(0)
	v_add_f32_e32 v57, v58, v57
	v_cndmask_b32_e32 v58, v59, v80, vcc
	ds_bpermute_b32 v58, v53, v58
	v_cndmask_b32_e32 v59, v80, v59, vcc
	s_waitcnt lgkmcnt(0)
	v_add_f32_e32 v58, v59, v58
	v_cndmask_b32_e32 v59, v61, v81, vcc
	ds_bpermute_b32 v59, v53, v59
	v_cndmask_b32_e32 v61, v81, v61, vcc
	s_waitcnt lgkmcnt(0)
	v_add_f32_e32 v59, v61, v59
	v_cndmask_b32_e32 v61, v60, v82, vcc
	ds_bpermute_b32 v61, v53, v61
	v_cndmask_b32_e32 v60, v82, v60, vcc
	s_waitcnt lgkmcnt(0)
	v_add_f32_e32 v60, v60, v61
	v_cndmask_b32_e32 v61, v67, v51, vcc
	ds_bpermute_b32 v61, v53, v61
	v_cndmask_b32_e32 v51, v51, v67, vcc
	s_waitcnt lgkmcnt(0)
	v_add_f32_e32 v51, v51, v61
	v_and_b32_e32 v61, 16, v50
	v_cmp_eq_u32_e32 vcc, 0, v61
	v_xor_b32_e32 v61, 64, v52
	s_nop 0
	v_cndmask_b32_e32 v62, v54, v58, vcc
	v_cndmask_b32_e32 v54, v58, v54, vcc
	ds_bpermute_b32 v58, v61, v62
	s_waitcnt lgkmcnt(0)
	v_add_f32_e32 v54, v54, v58
	v_cndmask_b32_e32 v58, v55, v59, vcc
	ds_bpermute_b32 v58, v61, v58
	v_cndmask_b32_e32 v55, v59, v55, vcc
	s_waitcnt lgkmcnt(0)
	v_add_f32_e32 v55, v55, v58
	v_cndmask_b32_e32 v58, v56, v60, vcc
	ds_bpermute_b32 v58, v61, v58
	v_cndmask_b32_e32 v56, v60, v56, vcc
	s_waitcnt lgkmcnt(0)
	v_add_f32_e32 v56, v56, v58
	v_cndmask_b32_e32 v58, v57, v51, vcc
	v_cndmask_b32_e32 v51, v51, v57, vcc
	ds_bpermute_b32 v57, v61, v58
	s_waitcnt lgkmcnt(0)
	v_add_f32_e32 v51, v51, v57
	v_and_b32_e32 v57, 8, v50
	v_cmp_eq_u32_e32 vcc, 0, v57
	v_xor_b32_e32 v57, 32, v52
	s_nop 0
	v_cndmask_b32_e32 v58, v54, v56, vcc
	v_cndmask_b32_e32 v54, v56, v54, vcc
	ds_bpermute_b32 v56, v57, v58
	s_waitcnt lgkmcnt(0)
	v_add_f32_e32 v54, v54, v56
	v_cndmask_b32_e32 v56, v55, v51, vcc
	v_cndmask_b32_e32 v51, v51, v55, vcc
	ds_bpermute_b32 v55, v57, v56
	s_waitcnt lgkmcnt(0)
	v_add_f32_e32 v51, v51, v55
	v_and_b32_e32 v55, 4, v50
	v_cmp_eq_u32_e32 vcc, 0, v55
	v_xor_b32_e32 v55, 16, v52
	s_nop 0
	v_cndmask_b32_e32 v56, v54, v51, vcc
	v_cndmask_b32_e32 v51, v51, v54, vcc
	ds_bpermute_b32 v54, v55, v56
	s_waitcnt lgkmcnt(0)
	v_add_f32_e32 v51, v54, v51
	v_xor_b32_e32 v54, 8, v52
	ds_bpermute_b32 v54, v54, v51
	v_xor_b32_e32 v52, 4, v52
	s_waitcnt lgkmcnt(0)
	v_add_f32_e32 v51, v51, v54
	ds_bpermute_b32 v52, v52, v51
	s_waitcnt lgkmcnt(0)
	v_add_f32_e32 v51, v51, v52
	ds_bpermute_b32 v52, v55, v51
	s_waitcnt lgkmcnt(0)
	v_max_f32_e32 v52, v52, v52
	v_max_f32_e32 v52, v51, v52
	ds_bpermute_b32 v54, v57, v52
	s_waitcnt lgkmcnt(0)
	v_max_f32_e32 v54, v54, v54
	v_max_f32_e32 v52, v52, v54
	ds_bpermute_b32 v54, v61, v52
	s_waitcnt lgkmcnt(0)
	v_max_f32_e32 v54, v54, v54
	v_max_f32_e32 v52, v52, v54
	ds_bpermute_b32 v54, v53, v52
	s_waitcnt lgkmcnt(0)
	v_max_f32_e32 v54, v54, v54
	v_max_f32_e32 v52, v52, v54
	v_sub_f32_e32 v51, v51, v52
	v_mul_f32_e32 v52, 0x3fb8aa3b, v51
	v_fma_f32 v54, v51, s76, -v52
	v_rndne_f32_e32 v56, v52
	v_fmac_f32_e32 v54, 0x32a5705f, v51
	v_sub_f32_e32 v52, v52, v56
	v_add_f32_e32 v52, v52, v54
	v_exp_f32_e32 v52, v52
	v_cvt_i32_f32_e32 v54, v56
	v_cmp_ngt_f32_e32 vcc, s64, v51
	v_ldexp_f32 v52, v52, v54
	s_nop 0
	v_cndmask_b32_e32 v52, 0, v52, vcc
	v_cmp_nlt_f32_e32 vcc, s65, v51
	s_nop 1
	v_cndmask_b32_e32 v51, v223, v52, vcc
	ds_bpermute_b32 v52, v55, v51
	s_waitcnt lgkmcnt(0)
	v_add_f32_e32 v52, v51, v52
	ds_bpermute_b32 v54, v57, v52
	s_waitcnt lgkmcnt(0)
	v_add_f32_e32 v52, v52, v54
	ds_bpermute_b32 v54, v61, v52
	s_waitcnt lgkmcnt(0)
	v_add_f32_e32 v52, v52, v54
	ds_bpermute_b32 v53, v53, v52
	v_and_b32_e32 v54, 3, v50
	v_cmp_eq_u32_e32 vcc, 0, v54
	s_and_saveexec_b64 s[8:9], vcc
	s_cbranch_execz .LBB0_1126
	s_waitcnt lgkmcnt(0)
	v_add_f32_e32 v52, v52, v53
	v_div_scale_f32 v53, s[10:11], v52, v52, v51
	v_rcp_f32_e32 v54, v53
	v_div_scale_f32 v55, vcc, v51, v52, v51
	v_and_b32_e32 v50, 60, v50
	v_fma_f32 v56, -v53, v54, 1.0
	v_fmac_f32_e32 v54, v56, v54
	v_mul_f32_e32 v56, v55, v54
	v_fma_f32 v57, -v53, v56, v55
	v_fmac_f32_e32 v56, v57, v54
	v_fma_f32 v53, -v53, v56, v55
	v_div_fmas_f32 v53, v53, v54, v56
	v_div_fixup_f32 v52, v53, v52, v51
	v_mov_b32_e32 v51, v0
	v_lshl_add_u64 v[50:51], v[68:69], 0, v[50:51]
	global_store_dword v[50:51], v52, off
	s_branch .LBB0_1126

.LBB0_1447:
	v_mov_b32_e32 v34, v139
	v_mov_b32_e32 v35, v130
	v_mov_b32_e32 v36, v138
	v_mov_b32_e32 v37, v131
	v_pk_add_f32 v[34:35], v[34:35], v[36:37]
	v_mov_b32_e32 v36, v129
	v_mov_b32_e32 v37, v136
	v_mov_b32_e32 v148, v128
	v_mov_b32_e32 v149, v137
	v_pk_add_f32 v[36:37], v[36:37], v[148:149]
	v_add_f32_e32 v1, v34, v35
	v_pk_add_f32 v[36:37], v[36:37], v[36:37] op_sel_hi:[0,1]
	v_add_f32_e32 v35, 0, v1
	v_add_f32_e32 v149, v126, v127
	v_add_f32_e32 v151, v134, v135
	v_mov_b32_e32 v148, v124
	v_mov_b32_e32 v150, v125
	v_mov_b32_e32 v36, v132
	v_mov_b32_e32 v34, v133
	v_pk_add_f32 v[148:149], v[148:149], v[150:151]
	v_pk_add_f32 v[34:35], v[36:37], v[34:35]
	s_mov_b32 s3, 0x800000
	v_pk_add_f32 v[34:35], v[148:149], v[34:35]
	s_lshl_b64 s[4:5], s[4:5], 11
	v_add_f32_e32 v1, v34, v35
	v_mov_b32_e32 v34, v0
	v_lshl_add_u64 v[152:153], v[58:59], 0, s[4:5]
	v_mbcnt_lo_u32_b32 v34, -1, v34
	v_mbcnt_hi_u32_b32 v34, -1, v34
	v_lshlrev_b32_e32 v34, 2, v34
	s_waitcnt lgkmcnt(0)
	s_nop 1
	v_add_f32_dpp v1, v1, v1 quad_perm:[1,0,3,2] row_mask:0xf bank_mask:0xf
	s_waitcnt lgkmcnt(0)
	s_nop 1
	v_add_f32_dpp v1, v1, v1 quad_perm:[2,3,0,1] row_mask:0xf bank_mask:0xf
	s_waitcnt lgkmcnt(0)
	s_nop 1
	v_add_f32_dpp v1, v1, v1 row_half_mirror row_mask:0xf bank_mask:0xf
	s_waitcnt lgkmcnt(0)
	s_nop 1
	v_add_f32_dpp v1, v1, v1 row_mirror row_mask:0xf bank_mask:0xf
	s_waitcnt lgkmcnt(0)
	v_mov_b32_e32 v35, v1
	v_mov_b32_e32 v34, v1
	s_nop 1
	v_permlane16_swap_b32 v35, v34
	s_nop 1
	v_add_f32_e32 v1, v35, v34
	s_waitcnt lgkmcnt(0)
	v_mov_b32_e32 v35, v1
	v_mov_b32_e32 v34, v1
	s_nop 1
	v_permlane32_swap_b32 v35, v34
	s_nop 1
	v_add_f32_e32 v1, v35, v34
	v_fmamk_f32 v35, v1, 0xba800000, v139
	v_fmamk_f32 v34, v1, 0xba800000, v138
	v_fmamk_f32 v131, v1, 0xba800000, v131
	v_fmac_f32_e32 v130, 0xba800000, v1
	v_pk_mul_f32 v[36:37], v[130:131], v[130:131]
	v_pk_mul_f32 v[138:139], v[34:35], v[34:35]
	v_fmamk_f32 v151, v1, 0xba800000, v137
	v_pk_mov_b32 v[148:149], v[138:139], v[36:37] op_sel:[1,0]
	v_mov_b32_e32 v139, v37
	v_fmamk_f32 v150, v1, 0xba800000, v136
	v_fmamk_f32 v129, v1, 0xba800000, v129
	v_fmac_f32_e32 v128, 0xba800000, v1
	v_pk_add_f32 v[36:37], v[148:149], v[138:139]
	v_pk_mul_f32 v[136:137], v[150:151], v[150:151]
	v_pk_mul_f32 v[138:139], v[128:129], v[128:129]
	v_pk_add_f32 v[36:37], v[36:37], v[36:37] op_sel_hi:[0,1]
	v_pk_mov_b32 v[148:149], v[138:139], v[136:137] op_sel:[1,0]
	v_mov_b32_e32 v139, v137
	v_fmac_f32_e32 v126, 0xba800000, v1
	v_pk_add_f32 v[136:137], v[148:149], v[138:139]
	v_fmamk_f32 v138, v1, 0xba800000, v134
	v_fmamk_f32 v127, v1, 0xba800000, v127
	v_mul_f32_e32 v36, v126, v126
	v_fmamk_f32 v139, v1, 0xba800000, v135
	v_pk_fma_f32 v[134:135], v[126:127], v[126:127], v[36:37] op_sel_hi:[1,1,0]
	v_mul_f32_e32 v36, v138, v138
	v_pk_add_f32 v[136:137], v[136:137], v[136:137] op_sel_hi:[0,1]
	v_pk_fma_f32 v[148:149], v[138:139], v[138:139], v[36:37] op_sel_hi:[1,1,0]
	v_fmamk_f32 v133, v1, 0xba800000, v133
	v_fmamk_f32 v132, v1, 0xba800000, v132
	v_fmamk_f32 v125, v1, 0xba800000, v125
	v_fmac_f32_e32 v124, 0xba800000, v1
	v_mul_f32_e32 v134, v124, v124
	v_mul_f32_e32 v148, v125, v125
	v_mul_f32_e32 v36, v132, v132
	v_mul_f32_e32 v136, v133, v133
	v_pk_add_f32 v[134:135], v[134:135], v[148:149]
	v_pk_add_f32 v[36:37], v[36:37], v[136:137]
	s_nop 0
	v_pk_add_f32 v[36:37], v[134:135], v[36:37]
	v_lshl_add_u64 v[134:135], v[56:57], 0, s[8:9]
	v_add_f32_e32 v1, v36, v37
	v_mov_b32_e32 v36, v0
	s_mov_b64 s[8:9], -1
	v_mbcnt_lo_u32_b32 v36, -1, v36
	v_mbcnt_hi_u32_b32 v36, -1, v36
	v_lshlrev_b32_e32 v36, 2, v36
	s_waitcnt lgkmcnt(0)
	s_nop 1
	v_add_f32_dpp v1, v1, v1 quad_perm:[1,0,3,2] row_mask:0xf bank_mask:0xf
	s_waitcnt lgkmcnt(0)
	s_nop 1
	v_add_f32_dpp v1, v1, v1 quad_perm:[2,3,0,1] row_mask:0xf bank_mask:0xf
	s_waitcnt lgkmcnt(0)
	s_nop 1
	v_add_f32_dpp v1, v1, v1 row_half_mirror row_mask:0xf bank_mask:0xf
	s_waitcnt lgkmcnt(0)
	s_nop 1
	v_add_f32_dpp v1, v1, v1 row_mirror row_mask:0xf bank_mask:0xf
	s_waitcnt lgkmcnt(0)
	v_mov_b32_e32 v37, v1
	v_mov_b32_e32 v36, v1
	s_nop 1
	v_permlane16_swap_b32 v37, v36
	s_nop 1
	v_add_f32_e32 v1, v37, v36
	s_waitcnt lgkmcnt(0)
	v_mov_b32_e32 v37, v1
	v_mov_b32_e32 v36, v1
	s_nop 1
	v_permlane32_swap_b32 v37, v36
	s_nop 1
	v_add_f32_e32 v1, v37, v36
	v_fmamk_f32 v1, v1, 0x3a800000, v217
	v_mul_f32_e32 v36, 0x4b800000, v1
	v_cmp_gt_f32_e32 vcc, s3, v1
	s_nop 1
	v_cndmask_b32_e32 v1, v1, v36, vcc
	v_rsq_f32_e32 v1, v1
	s_nop 0
	v_mul_f32_e32 v36, 0x45800000, v1
	v_cndmask_b32_e32 v136, v1, v36, vcc
	v_pk_mul_f32 v[34:35], v[34:35], v[136:137] op_sel_hi:[1,0]
	v_pk_mul_f32 v[36:37], v[130:131], v[136:137] op_sel_hi:[1,0]
	v_cndmask_b32_e64 v1, 0, 1, s[6:7]
	v_mov_b32_e32 v148, v136
	v_mov_b32_e32 v149, v136
	v_pk_fma_f32 v[36:37], v[4:5], v[36:37], v[12:13]
	v_pk_fma_f32 v[34:35], v[2:3], v[34:35], v[10:11]
	v_cmp_ne_u32_e64 s[4:5], 1, v1
	s_andn2_b64 vcc, exec, s[6:7]
	global_store_dwordx4 v[134:135], v[34:37], off
	s_cbranch_vccnz .LBB0_1449
	s_nop 0
	v_cvt_pk_bf16_f32 v34, v34, v35
	v_cvt_pk_bf16_f32 v35, v36, v37
	v_mov_b32_e32 v137, v136
	global_store_dwordx2 v[152:153], v[34:35], off
	v_pk_mul_f32 v[34:35], v[150:151], v[136:137]
	v_pk_mul_f32 v[130:131], v[128:129], v[148:149]
	v_pk_fma_f32 v[36:37], v[8:9], v[34:35], v[16:17]
	v_pk_fma_f32 v[34:35], v[6:7], v[130:131], v[14:15]
	s_mov_b64 s[8:9], 0
	global_store_dwordx4 v[134:135], v[34:37], off offset:1024
	s_nop 1
	v_cvt_pk_bf16_f32 v34, v34, v35
	v_cvt_pk_bf16_f32 v35, v36, v37
	global_store_dwordx2 v[152:153], v[34:35], off offset:512

.LBB0_1455:
	s_nop 1
	v_mov_b32_e32 v34, v47
	v_mov_b32_e32 v35, v142
	v_mov_b32_e32 v36, v46
	v_mov_b32_e32 v37, v143
	v_pk_add_f32 v[34:35], v[34:35], v[36:37]
	v_mov_b32_e32 v36, v43
	v_mov_b32_e32 v37, v140
	v_mov_b32_e32 v124, v42
	v_mov_b32_e32 v125, v141
	v_pk_add_f32 v[36:37], v[36:37], v[124:125]
	v_add_f32_e32 v1, v34, v35
	v_pk_add_f32 v[36:37], v[36:37], v[36:37] op_sel_hi:[0,1]
	v_add_f32_e32 v35, 0, v1
	v_add_f32_e32 v125, v38, v39
	v_add_f32_e32 v127, v48, v49
	v_mov_b32_e32 v124, v40
	v_mov_b32_e32 v126, v41
	v_mov_b32_e32 v36, v44
	v_mov_b32_e32 v34, v45
	v_pk_add_f32 v[124:125], v[124:125], v[126:127]
	v_pk_add_f32 v[34:35], v[36:37], v[34:35]
	s_andn2_b64 vcc, exec, s[12:13]
	v_pk_add_f32 v[34:35], v[124:125], v[34:35]
	s_nop 0
	v_add_f32_e32 v1, v34, v35
	v_mov_b32_e32 v34, v0
	s_nop 0
	v_mbcnt_lo_u32_b32 v34, -1, v34
	v_mbcnt_hi_u32_b32 v34, -1, v34
	v_lshlrev_b32_e32 v34, 2, v34
	s_waitcnt lgkmcnt(0)
	s_nop 1
	v_add_f32_dpp v1, v1, v1 quad_perm:[1,0,3,2] row_mask:0xf bank_mask:0xf
	s_waitcnt lgkmcnt(0)
	s_nop 1
	v_add_f32_dpp v1, v1, v1 quad_perm:[2,3,0,1] row_mask:0xf bank_mask:0xf
	s_waitcnt lgkmcnt(0)
	s_nop 1
	v_add_f32_dpp v1, v1, v1 row_half_mirror row_mask:0xf bank_mask:0xf
	s_waitcnt lgkmcnt(0)
	s_nop 1
	v_add_f32_dpp v1, v1, v1 row_mirror row_mask:0xf bank_mask:0xf
	s_waitcnt lgkmcnt(0)
	v_mov_b32_e32 v35, v1
	v_mov_b32_e32 v34, v1
	s_nop 1
	v_permlane16_swap_b32 v35, v34
	s_nop 1
	v_add_f32_e32 v1, v35, v34
	s_waitcnt lgkmcnt(0)
	v_mov_b32_e32 v35, v1
	v_mov_b32_e32 v34, v1
	s_nop 1
	v_permlane32_swap_b32 v35, v34
	s_nop 1
	v_add_f32_e32 v1, v35, v34
	v_fmamk_f32 v35, v1, 0xba800000, v143
	v_fmamk_f32 v47, v1, 0xba800000, v47
	v_fmamk_f32 v34, v1, 0xba800000, v142
	v_fmac_f32_e32 v46, 0xba800000, v1
	v_mul_f32_e32 v36, v47, v47
	v_mul_f32_e32 v37, v35, v35
	v_fmac_f32_e32 v36, v46, v46
	v_fmac_f32_e32 v37, v34, v34
	v_fmamk_f32 v129, v1, 0xba800000, v141
	v_fmamk_f32 v43, v1, 0xba800000, v43
	v_add_f32_e32 v36, v36, v37
	v_fmamk_f32 v128, v1, 0xba800000, v140
	v_fmac_f32_e32 v42, 0xba800000, v1
	v_mul_f32_e32 v37, v43, v43
	v_mul_f32_e32 v124, v129, v129
	v_fmac_f32_e32 v37, v42, v42
	v_fmac_f32_e32 v124, v128, v128
	v_add_f32_e32 v37, v37, v124
	v_fmamk_f32 v125, v1, 0xba800000, v49
	v_fmamk_f32 v39, v1, 0xba800000, v39
	v_add_f32_e32 v36, v36, v37
	v_fmamk_f32 v124, v1, 0xba800000, v48
	v_fmac_f32_e32 v38, 0xba800000, v1
	v_mul_f32_e32 v37, v39, v39
	v_mul_f32_e32 v48, v125, v125
	v_fmac_f32_e32 v37, v38, v38
	v_fmac_f32_e32 v48, v124, v124
	v_add_f32_e32 v37, v37, v48
	v_fmamk_f32 v45, v1, 0xba800000, v45
	v_fmamk_f32 v41, v1, 0xba800000, v41
	v_add_f32_e32 v36, v37, v36
	v_fmamk_f32 v44, v1, 0xba800000, v44
	v_fmac_f32_e32 v40, 0xba800000, v1
	v_mul_f32_e32 v1, v41, v41
	v_mul_f32_e32 v37, v45, v45
	v_fmac_f32_e32 v1, v40, v40
	v_fmac_f32_e32 v37, v44, v44
	v_add_f32_e32 v1, v1, v37
	v_add_f32_e32 v1, v1, v36
	v_mov_b32_e32 v36, v0
	s_nop 0
	v_mbcnt_lo_u32_b32 v36, -1, v36
	v_mbcnt_hi_u32_b32 v36, -1, v36
	v_lshlrev_b32_e32 v36, 2, v36
	s_waitcnt lgkmcnt(0)
	s_nop 1
	v_add_f32_dpp v1, v1, v1 quad_perm:[1,0,3,2] row_mask:0xf bank_mask:0xf
	s_waitcnt lgkmcnt(0)
	s_nop 1
	v_add_f32_dpp v1, v1, v1 quad_perm:[2,3,0,1] row_mask:0xf bank_mask:0xf
	s_waitcnt lgkmcnt(0)
	s_nop 1
	v_add_f32_dpp v1, v1, v1 row_half_mirror row_mask:0xf bank_mask:0xf
	s_waitcnt lgkmcnt(0)
	s_nop 1
	v_add_f32_dpp v1, v1, v1 row_mirror row_mask:0xf bank_mask:0xf
	s_waitcnt lgkmcnt(0)
	v_mov_b32_e32 v37, v1
	v_mov_b32_e32 v36, v1
	s_nop 1
	v_permlane16_swap_b32 v37, v36
	s_nop 1
	v_add_f32_e32 v1, v37, v36
	s_cbranch_vccnz .LBB0_1464
	s_waitcnt lgkmcnt(0)
	v_mov_b32_e32 v37, v1
	v_mov_b32_e32 v36, v1
	s_nop 1
	v_permlane32_swap_b32 v37, v36
	s_nop 1
	v_add_f32_e32 v1, v37, v36
	v_fmamk_f32 v1, v1, 0x3a800000, v217
	v_mul_f32_e32 v36, 0x4b800000, v1
	v_cmp_gt_f32_e32 vcc, s3, v1
	s_ashr_i32 s11, s10, 31
	s_lshl_b64 s[8:9], s[10:11], 12
	v_cndmask_b32_e32 v1, v1, v36, vcc
	v_rsq_f32_e32 v1, v1
	v_lshl_add_u64 v[48:49], v[56:57], 0, s[8:9]
	s_lshl_b64 s[8:9], s[10:11], 11
	v_lshl_add_u64 v[130:131], v[58:59], 0, s[8:9]
	v_mul_f32_e32 v36, 0x45800000, v1
	v_cndmask_b32_e32 v126, v1, v36, vcc
	v_mov_b32_e32 v132, v126
	v_mov_b32_e32 v133, v126
	v_pk_mul_f32 v[46:47], v[46:47], v[126:127] op_sel_hi:[1,0]
	v_pk_mul_f32 v[34:35], v[34:35], v[126:127] op_sel_hi:[1,0]
	s_mov_b64 s[8:9], -1
	v_pk_fma_f32 v[36:37], v[4:5], v[34:35], v[12:13]
	v_pk_fma_f32 v[34:35], v[2:3], v[46:47], v[10:11]
	s_and_b64 vcc, exec, s[4:5]
	v_pk_mul_f32 v[42:43], v[42:43], v[132:133]
	global_store_dwordx4 v[48:49], v[34:37], off
	s_cbranch_vccnz .LBB0_1458
	s_nop 0
	v_cvt_pk_bf16_f32 v34, v34, v35
	v_cvt_pk_bf16_f32 v35, v36, v37
	v_mov_b32_e32 v127, v126
	global_store_dwordx2 v[130:131], v[34:35], off
	v_pk_mul_f32 v[34:35], v[128:129], v[126:127]
	s_mov_b64 s[8:9], 0
	v_pk_fma_f32 v[36:37], v[8:9], v[34:35], v[16:17]
	v_pk_fma_f32 v[34:35], v[6:7], v[42:43], v[14:15]
	global_store_dwordx4 v[48:49], v[34:37], off offset:1024
	s_nop 1
	v_cvt_pk_bf16_f32 v34, v34, v35
	v_cvt_pk_bf16_f32 v35, v36, v37
	global_store_dwordx2 v[130:131], v[34:35], off offset:512

.LBB0_1500:
	v_mov_b32_e32 v34, v131
	v_mov_b32_e32 v35, v138
	v_mov_b32_e32 v36, v130
	v_mov_b32_e32 v37, v139
	v_pk_add_f32 v[34:35], v[34:35], v[36:37]
	v_mov_b32_e32 v36, v129
	v_mov_b32_e32 v37, v136
	v_mov_b32_e32 v148, v128
	v_mov_b32_e32 v149, v137
	v_pk_add_f32 v[36:37], v[36:37], v[148:149]
	v_add_f32_e32 v1, v34, v35
	v_pk_add_f32 v[36:37], v[36:37], v[36:37] op_sel_hi:[0,1]
	v_add_f32_e32 v35, 0, v1
	v_add_f32_e32 v149, v124, v125
	v_add_f32_e32 v151, v134, v135
	v_mov_b32_e32 v148, v126
	v_mov_b32_e32 v150, v127
	v_mov_b32_e32 v36, v132
	v_mov_b32_e32 v34, v133
	v_pk_add_f32 v[148:149], v[148:149], v[150:151]
	v_pk_add_f32 v[34:35], v[36:37], v[34:35]
	s_andn2_b64 vcc, exec, s[10:11]
	v_pk_add_f32 v[34:35], v[148:149], v[34:35]
	s_nop 0
	v_add_f32_e32 v1, v34, v35
	v_mov_b32_e32 v34, v0
	s_nop 0
	v_mbcnt_lo_u32_b32 v34, -1, v34
	v_mbcnt_hi_u32_b32 v34, -1, v34
	v_lshlrev_b32_e32 v34, 2, v34
	s_waitcnt lgkmcnt(0)
	s_nop 1
	v_add_f32_dpp v1, v1, v1 quad_perm:[1,0,3,2] row_mask:0xf bank_mask:0xf
	s_waitcnt lgkmcnt(0)
	s_nop 1
	v_add_f32_dpp v1, v1, v1 quad_perm:[2,3,0,1] row_mask:0xf bank_mask:0xf
	s_waitcnt lgkmcnt(0)
	s_nop 1
	v_add_f32_dpp v1, v1, v1 row_half_mirror row_mask:0xf bank_mask:0xf
	s_waitcnt lgkmcnt(0)
	s_nop 1
	v_add_f32_dpp v1, v1, v1 row_mirror row_mask:0xf bank_mask:0xf
	s_waitcnt lgkmcnt(0)
	v_mov_b32_e32 v35, v1
	v_mov_b32_e32 v34, v1
	s_nop 1
	v_permlane16_swap_b32 v35, v34
	s_nop 1
	v_add_f32_e32 v1, v35, v34
	s_waitcnt lgkmcnt(0)
	v_mov_b32_e32 v35, v1
	v_mov_b32_e32 v34, v1
	s_nop 1
	v_permlane32_swap_b32 v35, v34
	s_nop 1
	v_add_f32_e32 v1, v35, v34
	v_fmamk_f32 v35, v1, 0xba800000, v139
	v_fmamk_f32 v131, v1, 0xba800000, v131
	v_fmamk_f32 v34, v1, 0xba800000, v138
	v_fmac_f32_e32 v130, 0xba800000, v1
	v_mul_f32_e32 v36, v131, v131
	v_mul_f32_e32 v37, v35, v35
	v_fmac_f32_e32 v36, v130, v130
	v_fmac_f32_e32 v37, v34, v34
	v_fmamk_f32 v149, v1, 0xba800000, v137
	v_fmamk_f32 v129, v1, 0xba800000, v129
	v_add_f32_e32 v36, v36, v37
	v_fmamk_f32 v148, v1, 0xba800000, v136
	v_fmac_f32_e32 v128, 0xba800000, v1
	v_mul_f32_e32 v37, v129, v129
	v_mul_f32_e32 v136, v149, v149
	v_fmac_f32_e32 v37, v128, v128
	v_fmac_f32_e32 v136, v148, v148
	v_add_f32_e32 v37, v37, v136
	v_fmamk_f32 v137, v1, 0xba800000, v135
	v_fmamk_f32 v125, v1, 0xba800000, v125
	v_add_f32_e32 v36, v36, v37
	v_fmamk_f32 v136, v1, 0xba800000, v134
	v_fmac_f32_e32 v124, 0xba800000, v1
	v_mul_f32_e32 v37, v125, v125
	v_mul_f32_e32 v134, v137, v137
	v_fmac_f32_e32 v37, v124, v124
	v_fmac_f32_e32 v134, v136, v136
	v_add_f32_e32 v37, v37, v134
	v_fmamk_f32 v133, v1, 0xba800000, v133
	v_fmamk_f32 v127, v1, 0xba800000, v127
	v_add_f32_e32 v36, v37, v36
	v_fmamk_f32 v132, v1, 0xba800000, v132
	v_fmac_f32_e32 v126, 0xba800000, v1
	v_mul_f32_e32 v1, v127, v127
	v_mul_f32_e32 v37, v133, v133
	v_fmac_f32_e32 v1, v126, v126
	v_fmac_f32_e32 v37, v132, v132
	v_add_f32_e32 v1, v1, v37
	v_add_f32_e32 v1, v1, v36
	v_mov_b32_e32 v36, v0
	s_nop 0
	v_mbcnt_lo_u32_b32 v36, -1, v36
	v_mbcnt_hi_u32_b32 v36, -1, v36
	v_lshlrev_b32_e32 v36, 2, v36
	s_waitcnt lgkmcnt(0)
	s_nop 1
	v_add_f32_dpp v1, v1, v1 quad_perm:[1,0,3,2] row_mask:0xf bank_mask:0xf
	s_waitcnt lgkmcnt(0)
	s_nop 1
	v_add_f32_dpp v1, v1, v1 quad_perm:[2,3,0,1] row_mask:0xf bank_mask:0xf
	s_waitcnt lgkmcnt(0)
	s_nop 1
	v_add_f32_dpp v1, v1, v1 row_half_mirror row_mask:0xf bank_mask:0xf
	s_waitcnt lgkmcnt(0)
	s_nop 1
	v_add_f32_dpp v1, v1, v1 row_mirror row_mask:0xf bank_mask:0xf
	s_waitcnt lgkmcnt(0)
	v_mov_b32_e32 v37, v1
	v_mov_b32_e32 v36, v1
	s_nop 1
	v_permlane16_swap_b32 v37, v36
	s_nop 1
	v_add_f32_e32 v1, v37, v36
	s_cbranch_vccnz .LBB0_1509
	s_waitcnt lgkmcnt(0)
	v_mov_b32_e32 v37, v1
	v_mov_b32_e32 v36, v1
	s_nop 1
	v_permlane32_swap_b32 v37, v36
	s_nop 1
	v_add_f32_e32 v1, v37, v36
	v_fmamk_f32 v1, v1, 0x3a800000, v217
	s_mov_b32 s0, 0x800000
	v_mul_f32_e32 v36, 0x4b800000, v1
	v_cmp_gt_f32_e32 vcc, s0, v1
	s_ashr_i32 s9, s8, 31
	s_lshl_b64 s[0:1], s[8:9], 12
	v_cndmask_b32_e32 v1, v1, v36, vcc
	v_rsq_f32_e32 v1, v1
	v_lshl_add_u64 v[134:135], v[56:57], 0, s[0:1]
	s_lshl_b64 s[0:1], s[8:9], 11
	v_lshl_add_u64 v[150:151], v[58:59], 0, s[0:1]
	v_mul_f32_e32 v36, 0x45800000, v1
	v_cndmask_b32_e32 v138, v1, v36, vcc
	v_mov_b32_e32 v152, v138
	v_mov_b32_e32 v153, v138
	v_pk_mul_f32 v[130:131], v[130:131], v[138:139] op_sel_hi:[1,0]
	v_pk_mul_f32 v[34:35], v[34:35], v[138:139] op_sel_hi:[1,0]
	s_mov_b64 s[0:1], -1
	v_pk_fma_f32 v[36:37], v[4:5], v[34:35], v[12:13]
	v_pk_fma_f32 v[34:35], v[2:3], v[130:131], v[10:11]
	s_and_b64 vcc, exec, s[4:5]
	v_pk_mul_f32 v[128:129], v[128:129], v[152:153]
	global_store_dwordx4 v[134:135], v[34:37], off
	s_cbranch_vccnz .LBB0_1503
	s_nop 0
	v_cvt_pk_bf16_f32 v34, v34, v35
	v_cvt_pk_bf16_f32 v35, v36, v37
	v_mov_b32_e32 v139, v138
	global_store_dwordx2 v[150:151], v[34:35], off
	v_pk_mul_f32 v[34:35], v[148:149], v[138:139]
	s_mov_b64 s[0:1], 0
	v_pk_fma_f32 v[36:37], v[8:9], v[34:35], v[16:17]
	v_pk_fma_f32 v[34:35], v[6:7], v[128:129], v[14:15]
	global_store_dwordx4 v[134:135], v[34:37], off offset:1024
	s_nop 1
	v_cvt_pk_bf16_f32 v34, v34, v35
	v_cvt_pk_bf16_f32 v35, v36, v37
	global_store_dwordx2 v[150:151], v[34:35], off offset:512

.LBB0_1509:
	s_nop 1
	v_mov_b32_e32 v34, v47
	v_mov_b32_e32 v35, v142
	s_waitcnt lgkmcnt(0)
	v_mov_b32_e32 v36, v46
	v_mov_b32_e32 v37, v143
	v_pk_add_f32 v[34:35], v[34:35], v[36:37]
	v_mov_b32_e32 v36, v43
	v_mov_b32_e32 v37, v140
	v_mov_b32_e32 v124, v42
	v_mov_b32_e32 v125, v141
	v_pk_add_f32 v[36:37], v[36:37], v[124:125]
	v_add_f32_e32 v1, v34, v35
	v_pk_add_f32 v[36:37], v[36:37], v[36:37] op_sel_hi:[0,1]
	v_add_f32_e32 v35, 0, v1
	v_add_f32_e32 v125, v38, v39
	v_add_f32_e32 v127, v48, v49
	v_mov_b32_e32 v124, v40
	v_mov_b32_e32 v126, v41
	v_mov_b32_e32 v36, v44
	v_mov_b32_e32 v34, v45
	v_pk_add_f32 v[124:125], v[124:125], v[126:127]
	v_pk_add_f32 v[34:35], v[36:37], v[34:35]
	s_andn2_b64 vcc, exec, s[14:15]
	v_pk_add_f32 v[34:35], v[124:125], v[34:35]
	s_nop 0
	v_add_f32_e32 v1, v34, v35
	v_mov_b32_e32 v34, v0
	s_nop 0
	v_mbcnt_lo_u32_b32 v34, -1, v34
	v_mbcnt_hi_u32_b32 v34, -1, v34
	v_lshlrev_b32_e32 v34, 2, v34
	s_waitcnt lgkmcnt(0)
	s_nop 1
	v_add_f32_dpp v1, v1, v1 quad_perm:[1,0,3,2] row_mask:0xf bank_mask:0xf
	s_waitcnt lgkmcnt(0)
	s_nop 1
	v_add_f32_dpp v1, v1, v1 quad_perm:[2,3,0,1] row_mask:0xf bank_mask:0xf
	s_waitcnt lgkmcnt(0)
	s_nop 1
	v_add_f32_dpp v1, v1, v1 row_half_mirror row_mask:0xf bank_mask:0xf
	s_waitcnt lgkmcnt(0)
	s_nop 1
	v_add_f32_dpp v1, v1, v1 row_mirror row_mask:0xf bank_mask:0xf
	s_waitcnt lgkmcnt(0)
	v_mov_b32_e32 v35, v1
	v_mov_b32_e32 v34, v1
	s_nop 1
	v_permlane16_swap_b32 v35, v34
	s_nop 1
	v_add_f32_e32 v1, v35, v34
	s_waitcnt lgkmcnt(0)
	v_mov_b32_e32 v35, v1
	v_mov_b32_e32 v34, v1
	s_nop 1
	v_permlane32_swap_b32 v35, v34
	s_nop 1
	v_add_f32_e32 v1, v35, v34
	v_fmamk_f32 v35, v1, 0xba800000, v143
	v_fmamk_f32 v47, v1, 0xba800000, v47
	v_fmamk_f32 v34, v1, 0xba800000, v142
	v_fmac_f32_e32 v46, 0xba800000, v1
	v_mul_f32_e32 v36, v47, v47
	v_mul_f32_e32 v37, v35, v35
	v_fmac_f32_e32 v36, v46, v46
	v_fmac_f32_e32 v37, v34, v34
	v_fmamk_f32 v129, v1, 0xba800000, v141
	v_fmamk_f32 v43, v1, 0xba800000, v43
	v_add_f32_e32 v36, v36, v37
	v_fmamk_f32 v128, v1, 0xba800000, v140
	v_fmac_f32_e32 v42, 0xba800000, v1
	v_mul_f32_e32 v37, v43, v43
	v_mul_f32_e32 v124, v129, v129
	v_fmac_f32_e32 v37, v42, v42
	v_fmac_f32_e32 v124, v128, v128
	v_add_f32_e32 v37, v37, v124
	v_fmamk_f32 v125, v1, 0xba800000, v49
	v_fmamk_f32 v39, v1, 0xba800000, v39
	v_add_f32_e32 v36, v36, v37
	v_fmamk_f32 v124, v1, 0xba800000, v48
	v_fmac_f32_e32 v38, 0xba800000, v1
	v_mul_f32_e32 v37, v39, v39
	v_mul_f32_e32 v48, v125, v125
	v_fmac_f32_e32 v37, v38, v38
	v_fmac_f32_e32 v48, v124, v124
	v_add_f32_e32 v37, v37, v48
	v_fmamk_f32 v45, v1, 0xba800000, v45
	v_fmamk_f32 v41, v1, 0xba800000, v41
	v_add_f32_e32 v36, v37, v36
	v_fmamk_f32 v44, v1, 0xba800000, v44
	v_fmac_f32_e32 v40, 0xba800000, v1
	v_mul_f32_e32 v1, v41, v41
	v_mul_f32_e32 v37, v45, v45
	v_fmac_f32_e32 v1, v40, v40
	v_fmac_f32_e32 v37, v44, v44
	v_add_f32_e32 v1, v1, v37
	v_add_f32_e32 v1, v1, v36
	v_mov_b32_e32 v36, v0
	s_nop 0
	v_mbcnt_lo_u32_b32 v36, -1, v36
	v_mbcnt_hi_u32_b32 v36, -1, v36
	v_lshlrev_b32_e32 v36, 2, v36
	s_waitcnt lgkmcnt(0)
	s_nop 1
	v_add_f32_dpp v1, v1, v1 quad_perm:[1,0,3,2] row_mask:0xf bank_mask:0xf
	s_waitcnt lgkmcnt(0)
	s_nop 1
	v_add_f32_dpp v1, v1, v1 quad_perm:[2,3,0,1] row_mask:0xf bank_mask:0xf
	s_waitcnt lgkmcnt(0)
	s_nop 1
	v_add_f32_dpp v1, v1, v1 row_half_mirror row_mask:0xf bank_mask:0xf
	s_waitcnt lgkmcnt(0)
	s_nop 1
	v_add_f32_dpp v1, v1, v1 row_mirror row_mask:0xf bank_mask:0xf
	s_waitcnt lgkmcnt(0)
	v_mov_b32_e32 v37, v1
	v_mov_b32_e32 v36, v1
	s_nop 1
	v_permlane16_swap_b32 v37, v36
	s_nop 1
	v_add_f32_e32 v1, v37, v36
	s_cbranch_vccnz .LBB0_1408
	s_waitcnt lgkmcnt(0)
	v_mov_b32_e32 v37, v1
	v_mov_b32_e32 v36, v1
	s_nop 1
	v_permlane32_swap_b32 v37, v36
	s_nop 1
	v_add_f32_e32 v1, v37, v36
	v_fmamk_f32 v1, v1, 0x3a800000, v217
	s_mov_b32 s0, 0x800000
	v_mul_f32_e32 v36, 0x4b800000, v1
	v_cmp_gt_f32_e32 vcc, s0, v1
	s_ashr_i32 s13, s12, 31
	s_lshl_b64 s[0:1], s[12:13], 12
	v_cndmask_b32_e32 v1, v1, v36, vcc
	v_rsq_f32_e32 v1, v1
	v_lshl_add_u64 v[48:49], v[56:57], 0, s[0:1]
	s_lshl_b64 s[0:1], s[12:13], 11
	v_lshl_add_u64 v[130:131], v[58:59], 0, s[0:1]
	v_mul_f32_e32 v36, 0x45800000, v1
	v_cndmask_b32_e32 v126, v1, v36, vcc
	v_mov_b32_e32 v132, v126
	v_mov_b32_e32 v133, v126
	v_pk_mul_f32 v[46:47], v[46:47], v[126:127] op_sel_hi:[1,0]
	v_pk_mul_f32 v[34:35], v[34:35], v[126:127] op_sel_hi:[1,0]
	s_mov_b64 s[0:1], -1
	v_pk_fma_f32 v[36:37], v[4:5], v[34:35], v[12:13]
	v_pk_fma_f32 v[34:35], v[2:3], v[46:47], v[10:11]
	s_and_b64 vcc, exec, s[4:5]
	v_pk_mul_f32 v[42:43], v[42:43], v[132:133]
	global_store_dwordx4 v[48:49], v[34:37], off
	s_cbranch_vccnz .LBB0_1512
	s_nop 0
	v_cvt_pk_bf16_f32 v34, v34, v35
	v_cvt_pk_bf16_f32 v35, v36, v37
	v_mov_b32_e32 v127, v126
	global_store_dwordx2 v[130:131], v[34:35], off
	v_pk_mul_f32 v[34:35], v[128:129], v[126:127]
	s_mov_b64 s[0:1], 0
	v_pk_fma_f32 v[36:37], v[8:9], v[34:35], v[16:17]
	v_pk_fma_f32 v[34:35], v[6:7], v[42:43], v[14:15]
	global_store_dwordx4 v[48:49], v[34:37], off offset:1024
	s_nop 1
	v_cvt_pk_bf16_f32 v34, v34, v35
	v_cvt_pk_bf16_f32 v35, v36, v37
	global_store_dwordx2 v[130:131], v[34:35], off offset:512
